# D1: next item's 16 row loads issued after the conv-weight/halo loads and kept in flight behind a counted vmcnt(16) (was vmcnt(0) draining them before every item)
# baseline (speedup 1.0000x reference)
; #define D1_LOAD(RH, RV, IT) do { const int it_ = (IT); const int s_ = it_ % 6, m0_ = (it_ / 6) * 16, ch_ = 512 * s_ + 8 * lane; \
;         _Pragma("unroll") for (int tt = 0; tt < 16; ++tt) RV[tt] = *(gcu)(PROJ + (size_t)(m0_ + tt) * NPROJ + ch_); } while (0)
; DI void d1_phase(const Params& P, int l, int gw, int NGW, int lane) {
;     ...
;         if (it + NGW < NIT) D1_LOAD(hB, vB, it + NGW);
.LBB0_496:
	s_add_i32 s19, s23, s14
	s_cmpk_lt_i32 s19, 0x1800
	s_cselect_b64 s[40:41], -1, 0
	s_cmpk_gt_i32 s19, 0x17ff
	s_mul_hi_i32 s15, s19, 0x2aaaaaab
	s_cbranch_scc1 .LBB0_498
	s_lshr_b32 s0, s15, 31
	s_add_i32 s0, s15, s0
	s_mul_i32 s1, s0, 6
	s_sub_i32 s1, s19, s1
	s_lshl_b32 s8, s0, 4
	v_lshl_or_b32 v64, s1, 9, v191
	v_readlane_b32 s0, v255, 6
	v_ashrrev_i32_e32 v65, 31, v64
	v_readlane_b32 s1, v255, 7
	s_nop 1
	v_lshl_add_u64 v[122:123], v[64:65], 1, s[0:1]
	v_mad_i64_i32 v[64:65], s[0:1], s8, v237, v[122:123]
	s_or_b32 s0, s8, 1
	s_nop 0
	v_mad_i64_i32 v[68:69], s[0:1], s0, v237, v[122:123]
	s_or_b32 s0, s8, 2
	s_nop 0
	v_mad_i64_i32 v[72:73], s[0:1], s0, v237, v[122:123]
	s_or_b32 s0, s8, 3
	s_nop 0
	v_mad_i64_i32 v[76:77], s[0:1], s0, v237, v[122:123]
	s_or_b32 s0, s8, 4
	s_nop 0
	v_mad_i64_i32 v[80:81], s[0:1], s0, v237, v[122:123]
	s_or_b32 s0, s8, 5
	s_nop 0
	v_mad_i64_i32 v[84:85], s[0:1], s0, v237, v[122:123]
	s_or_b32 s0, s8, 6
	s_nop 0
	v_mad_i64_i32 v[88:89], s[0:1], s0, v237, v[122:123]
	s_or_b32 s0, s8, 7
	s_nop 0
	v_mad_i64_i32 v[92:93], s[0:1], s0, v237, v[122:123]
	s_or_b32 s0, s8, 8
	s_nop 0
	v_mad_i64_i32 v[98:99], s[0:1], s0, v237, v[122:123]
	s_or_b32 s0, s8, 9
	s_nop 0
	v_mad_i64_i32 v[102:103], s[0:1], s0, v237, v[122:123]
	s_or_b32 s0, s8, 10
	s_nop 0
	v_mad_i64_i32 v[106:107], s[0:1], s0, v237, v[122:123]
	s_or_b32 s0, s8, 11
	s_nop 0
	v_mad_i64_i32 v[110:111], s[0:1], s0, v237, v[122:123]
	s_or_b32 s0, s8, 12
	s_nop 0
	v_mad_i64_i32 v[114:115], s[0:1], s0, v237, v[122:123]
	s_or_b32 s0, s8, 13
	s_nop 0
	v_mad_i64_i32 v[118:119], s[0:1], s0, v237, v[122:123]
	s_or_b32 s0, s8, 14
	s_nop 0
	v_mad_i64_i32 v[124:125], s[0:1], s0, v237, v[122:123]
	s_or_b32 s0, s8, 15
	s_nop 0
	v_mad_i64_i32 v[126:127], s[0:1], s0, v237, v[122:123]
	s_movk_i32 s1, 0x3000

.LBB0_505:
	s_cmp_eq_u64 s[40:41], 0
	s_cbranch_scc1 .Ld1a_nonext
	global_load_dwordx4 v[64:67], v[64:65], off
	global_load_dwordx4 v[68:71], v[68:69], off
	global_load_dwordx4 v[72:75], v[72:73], off
	global_load_dwordx4 v[76:79], v[76:77], off
	global_load_dwordx4 v[80:83], v[80:81], off
	global_load_dwordx4 v[84:87], v[84:85], off
	global_load_dwordx4 v[88:91], v[88:89], off
	global_load_dwordx4 v[92:95], v[92:93], off
	global_load_dwordx4 v[98:101], v[98:99], off
	global_load_dwordx4 v[102:105], v[102:103], off
	global_load_dwordx4 v[106:109], v[106:107], off
	global_load_dwordx4 v[110:113], v[110:111], off
	global_load_dwordx4 v[114:117], v[114:115], off
	global_load_dwordx4 v[118:121], v[118:119], off
	global_load_dwordx4 v[122:125], v[124:125], off
	global_load_dwordx4 v[126:129], v[126:127], off
	s_waitcnt vmcnt(16)
	s_branch .Ld1a_go

.Ld1a_go:
	v_lshlrev_b32_e32 v206, 16, v170
	v_and_b32_e32 v207, 0xffff0000, v170
	v_and_b32_e32 v205, 0xffff0000, v171
	v_lshlrev_b32_e32 v204, 16, v171
	v_and_b32_e32 v181, 0xffff0000, v172
	v_lshlrev_b32_e32 v180, 16, v172
	v_and_b32_e32 v171, 0xffff0000, v173
	v_lshlrev_b32_e32 v170, 16, v173
	v_lshlrev_b32_e32 v172, 16, v162
	v_and_b32_e32 v173, 0xffff0000, v162
	v_pk_mul_f32 v[202:203], v[150:151], v[206:207]
	v_lshlrev_b32_e32 v208, 16, v166
	v_and_b32_e32 v209, 0xffff0000, v166
	v_pk_fma_f32 v[172:173], v[146:147], v[172:173], v[202:203]
	v_lshlrev_b32_e32 v196, 16, v0
	v_and_b32_e32 v197, 0xffff0000, v0
	v_pk_fma_f32 v[172:173], v[154:155], v[208:209], v[172:173]
	v_and_b32_e32 v177, 0xffff0000, v169
	v_pk_fma_f32 v[172:173], v[158:159], v[196:197], v[172:173]
	v_lshlrev_b32_e32 v176, 16, v169
	v_mul_f32_e32 v169, 0xbfb8aa3b, v172
	v_exp_f32_e32 v169, v169
	v_and_b32_e32 v185, 0xffff0000, v163
	v_lshlrev_b32_e32 v184, 16, v163
	v_and_b32_e32 v201, 0xffff0000, v167
	v_add_f32_e32 v169, 1.0, v169
	v_rcp_f32_e32 v202, v169
	v_mul_f32_e32 v169, 0xbfb8aa3b, v173
	v_exp_f32_e32 v169, v169
	v_lshlrev_b32_e32 v200, 16, v167
	v_and_b32_e32 v175, 0xffff0000, v1
	v_lshlrev_b32_e32 v174, 16, v1
	v_add_f32_e32 v169, 1.0, v169
	v_rcp_f32_e32 v203, v169
	v_and_b32_e32 v163, 0xffff0000, v164
	v_lshlrev_b32_e32 v162, 16, v164
	v_and_b32_e32 v199, 0xffff0000, v168
	v_pk_mul_f32 v[172:173], v[172:173], v[202:203]
	v_pk_mul_f32 v[202:203], v[152:153], v[204:205]
	v_lshlrev_b32_e32 v198, 16, v168
	v_pk_fma_f32 v[184:185], v[148:149], v[184:185], v[202:203]
	v_and_b32_e32 v167, 0xffff0000, v2
	v_pk_fma_f32 v[184:185], v[156:157], v[200:201], v[184:185]
	v_lshlrev_b32_e32 v166, 16, v2
	v_pk_fma_f32 v[184:185], v[160:161], v[174:175], v[184:185]
	v_and_b32_e32 v187, 0xffff0000, v165
	v_mul_f32_e32 v169, 0xbfb8aa3b, v184
	v_exp_f32_e32 v169, v169
	v_lshlrev_b32_e32 v186, 16, v165
	v_and_b32_e32 v165, 0xffff0000, v3
	v_lshlrev_b32_e32 v164, 16, v3
	v_add_f32_e32 v169, 1.0, v169
	v_rcp_f32_e32 v202, v169
	v_mul_f32_e32 v169, 0xbfb8aa3b, v185
	v_exp_f32_e32 v169, v169
	s_mul_i32 s22, s22, -6
	s_add_i32 s0, s14, s22
	s_ashr_i32 s22, s0, 1
	v_add_f32_e32 v169, 1.0, v169
	v_rcp_f32_e32 v203, v169
	s_cmp_lt_u32 s0, 2
	s_cselect_b64 vcc, -1, 0
	s_cmp_lt_i32 s22, 2
	v_pk_mul_f32 v[202:203], v[184:185], v[202:203]
	v_pk_mul_f32 v[184:185], v[134:135], v[180:181]
	s_cselect_b64 s[8:9], -1, 0
	v_pk_fma_f32 v[162:163], v[130:131], v[162:163], v[184:185]
	s_cmp_gt_i32 s22, 1
	v_pk_fma_f32 v[162:163], v[138:139], v[198:199], v[162:163]
	v_mov_b32_e32 v168, 1.0
	v_pk_fma_f32 v[162:163], v[142:143], v[166:167], v[162:163]
	v_cndmask_b32_e32 v219, 1.0, v238, vcc
	v_mul_f32_e32 v169, 0xbfb8aa3b, v162
	v_exp_f32_e32 v169, v169
	v_mov_b32_e32 v214, 1.0
	v_add_f32_e32 v169, 1.0, v169
	v_rcp_f32_e32 v184, v169
	v_mul_f32_e32 v169, 0xbfb8aa3b, v163
	v_exp_f32_e32 v169, v169
	s_nop 0
	v_add_f32_e32 v169, 1.0, v169
	v_rcp_f32_e32 v185, v169
	s_nop 0
	v_pk_mul_f32 v[210:211], v[162:163], v[184:185]
	v_pk_mul_f32 v[162:163], v[136:137], v[170:171]
	s_nop 0
	v_pk_fma_f32 v[162:163], v[132:133], v[186:187], v[162:163]
	s_nop 0
	v_pk_fma_f32 v[162:163], v[140:141], v[176:177], v[162:163]
	s_nop 0
	v_pk_fma_f32 v[162:163], v[144:145], v[164:165], v[162:163]
	s_nop 0
	v_mul_f32_e32 v169, 0xbfb8aa3b, v162
	v_exp_f32_e32 v169, v169
	s_nop 0
	v_add_f32_e32 v169, 1.0, v169
	v_rcp_f32_e32 v184, v169
	v_mul_f32_e32 v169, 0xbfb8aa3b, v163
	v_exp_f32_e32 v169, v169
	s_nop 0
	v_add_f32_e32 v169, 1.0, v169
	v_rcp_f32_e32 v185, v169
	s_nop 0
	v_pk_mul_f32 v[212:213], v[162:163], v[184:185]
	s_cbranch_scc1 .LBB0_507
	v_pk_mul_f32 v[162:163], v[172:173], v[172:173]
	v_pk_mul_f32 v[184:185], v[202:203], v[202:203]
	v_add_f32_e32 v162, v162, v163
	v_add_f32_e32 v162, v184, v162
	v_pk_mul_f32 v[186:187], v[210:211], v[210:211]
	v_add_f32_e32 v162, v185, v162
	v_and_b32_e32 v169, 64, v232
	v_add_f32_e32 v162, v186, v162
	v_xor_b32_e32 v163, 1, v232
	v_add_u32_e32 v169, 64, v169
	v_pk_mul_f32 v[214:215], v[212:213], v[212:213]
	v_add_f32_e32 v162, v187, v162
	v_cmp_lt_i32_e64 s[0:1], v163, v169
	v_add_f32_e32 v162, v214, v162
	v_add_f32_e32 v162, v215, v162
	v_cndmask_b32_e64 v163, v232, v163, s[0:1]
	v_lshlrev_b32_e32 v163, 2, v163
	ds_bpermute_b32 v163, v163, v162
	s_waitcnt lgkmcnt(0)
	v_add_f32_e32 v162, v162, v163
	v_xor_b32_e32 v163, 2, v232
	v_cmp_lt_i32_e64 s[0:1], v163, v169
	s_nop 1
	v_cndmask_b32_e64 v163, v232, v163, s[0:1]
	v_lshlrev_b32_e32 v163, 2, v163
	ds_bpermute_b32 v163, v163, v162
	s_waitcnt lgkmcnt(0)
	v_add_f32_e32 v162, v162, v163
	v_xor_b32_e32 v163, 4, v232
	v_cmp_lt_i32_e64 s[0:1], v163, v169
	s_nop 1
	v_cndmask_b32_e64 v163, v232, v163, s[0:1]
	v_lshlrev_b32_e32 v163, 2, v163
	ds_bpermute_b32 v163, v163, v162
	s_waitcnt lgkmcnt(0)
	v_add_f32_e32 v162, v162, v163
	v_xor_b32_e32 v163, 8, v232
	v_cmp_lt_i32_e64 s[0:1], v163, v169
	s_nop 1
	v_cndmask_b32_e64 v163, v232, v163, s[0:1]
	v_lshlrev_b32_e32 v163, 2, v163
	ds_bpermute_b32 v163, v163, v162
	s_waitcnt lgkmcnt(0)
	v_add_f32_e32 v162, v162, v163
	v_add_f32_e32 v162, 0x358637bd, v162
	v_rsq_f32_e32 v162, v162
	s_nop 0
	v_mul_f32_e32 v214, v219, v162

; #define D1_LOAD(RH, RV, IT) do { const int it_ = (IT); const int s_ = it_ % 6, m0_ = (it_ / 6) * 16, ch_ = 512 * s_ + 8 * lane; \
;         _Pragma("unroll") for (int tt = 0; tt < 16; ++tt) RV[tt] = *(gcu)(PROJ + (size_t)(m0_ + tt) * NPROJ + ch_); } while (0)
; DI void d1_phase(const Params& P, int l, int gw, int NGW, int lane) {
;     ...
;     u32x4 vA[16], vB[16]; int hA = 0, hB = 0; (void)hA; (void)hB;
;     if (gw < NIT) D1_LOAD(hA, vA, gw);
; #pragma unroll 1
;     for (int it = gw; it < NIT; it += 2 * NGW) {
;         if (it + NGW < NIT) D1_LOAD(hB, vB, it + NGW);
;         D1_COMPUTE(hA, vA, it);
;         if (it + NGW < NIT) {
;             if (it + 2 * NGW < NIT) D1_LOAD(hA, vA, it + 2 * NGW);
.LBB0_537:
	v_pk_mul_f32 v[130:131], v[130:131], v[168:169] op_sel_hi:[1,0]
	v_pk_mul_f32 v[136:137], v[146:147], v[168:169] op_sel_hi:[1,0]
	v_pk_mul_f32 v[132:133], v[132:133], v[168:169] op_sel_hi:[1,0]
	v_cvt_pk_bf16_f32 v138, v130, v131
	v_pk_mul_f32 v[130:131], v[134:135], v[168:169] op_sel_hi:[1,0]
	v_readlane_b32 s0, v252, 60
	v_cvt_pk_bf16_f32 v136, v136, v137
	v_cvt_pk_bf16_f32 v137, v132, v133
	v_cvt_pk_bf16_f32 v139, v130, v131
	s_andn2_b64 vcc, exec, s[40:41]
	s_add_i32 s14, s14, s0
	global_store_dwordx4 v[162:163], v[136:139], off offset:3840
	s_cbranch_vccnz .LBB0_495
	s_movk_i32 s9, 0x3000
	s_cmpk_gt_i32 s14, 0x17ff
	s_cbranch_scc1 .LBB0_540
	s_mul_hi_i32 s0, s14, 0x2aaaaaab
	s_lshr_b32 s1, s0, 31
	s_add_i32 s0, s0, s1
	s_lshl_b32 s8, s0, 4
	s_mulk_i32 s0, 0xf400
	s_add_i32 s0, s0, s12
	v_add_u32_e32 v0, s0, v218
	v_readlane_b32 s0, v255, 6
	v_ashrrev_i32_e32 v1, 31, v0
	v_readlane_b32 s1, v255, 7
	s_nop 1
	v_lshl_add_u64 v[56:57], v[0:1], 1, s[0:1]
	v_mad_i64_i32 v[0:1], s[0:1], s8, v237, v[56:57]
	s_or_b32 s0, s8, 1
	s_nop 0
	v_mad_i64_i32 v[4:5], s[0:1], s0, v237, v[56:57]
	s_or_b32 s0, s8, 2
	s_nop 0
	v_mad_i64_i32 v[8:9], s[0:1], s0, v237, v[56:57]
	s_or_b32 s0, s8, 3
	s_nop 0
	v_mad_i64_i32 v[12:13], s[0:1], s0, v237, v[56:57]
	s_or_b32 s0, s8, 4
	s_nop 0
	v_mad_i64_i32 v[16:17], s[0:1], s0, v237, v[56:57]
	s_or_b32 s0, s8, 5
	s_nop 0
	v_mad_i64_i32 v[20:21], s[0:1], s0, v237, v[56:57]
	s_or_b32 s0, s8, 6
	s_nop 0
	v_mad_i64_i32 v[24:25], s[0:1], s0, v237, v[56:57]
	s_or_b32 s0, s8, 7
	s_nop 0
	v_mad_i64_i32 v[28:29], s[0:1], s0, v237, v[56:57]
	s_or_b32 s0, s8, 8
	s_nop 0
	v_mad_i64_i32 v[32:33], s[0:1], s0, v237, v[56:57]
	s_or_b32 s0, s8, 9
	s_nop 0
	v_mad_i64_i32 v[36:37], s[0:1], s0, v237, v[56:57]
	s_or_b32 s0, s8, 10
	s_nop 0
	v_mad_i64_i32 v[40:41], s[0:1], s0, v237, v[56:57]
	s_or_b32 s0, s8, 11
	s_nop 0
	v_mad_i64_i32 v[44:45], s[0:1], s0, v237, v[56:57]
	s_or_b32 s0, s8, 12
	s_nop 0
	v_mad_i64_i32 v[48:49], s[0:1], s0, v237, v[56:57]
	s_or_b32 s0, s8, 13
	s_nop 0
	v_mad_i64_i32 v[52:53], s[0:1], s0, v237, v[56:57]
	s_or_b32 s0, s8, 14
	s_nop 0
	v_mad_i64_i32 v[58:59], s[0:1], s0, v237, v[56:57]
	s_or_b32 s0, s8, 15
	s_nop 0
	v_mad_i64_i32 v[60:61], s[0:1], s0, v237, v[56:57]
.LBB0_540:
	s_lshr_b32 s11, s15, 31
	s_add_i32 s0, s15, s11
	s_mul_i32 s1, s0, 6
	s_sub_i32 s20, s19, s1
	v_lshl_or_b32 v178, s20, 9, v191
	v_ashrrev_i32_e32 v179, 31, v178
	v_lshl_add_u64 v[142:143], v[178:179], 2, s[4:5]
	v_add_co_u32_e32 v136, vcc, s9, v142
	s_movk_i32 s1, 0x6000
	s_nop 0
	v_addc_co_u32_e32 v137, vcc, 0, v143, vcc
	s_mov_b64 s[8:9], 0x6000
	v_add_co_u32_e32 v140, vcc, s1, v142
	s_mov_b64 s[36:37], 0x3000
	v_lshl_add_u64 v[138:139], v[142:143], 0, s[8:9]
	v_addc_co_u32_e32 v141, vcc, 0, v143, vcc
	s_mov_b64 s[8:9], 0x9000
	s_mov_b32 s1, 0x9000
	global_load_dwordx4 v[130:133], v[142:143], off offset:16
	global_load_dwordx4 v[146:149], v[142:143], off
	v_lshl_add_u64 v[134:135], v[142:143], 0, s[36:37]
	v_lshl_add_u64 v[144:145], v[142:143], 0, s[8:9]
	v_add_co_u32_e32 v142, vcc, s1, v142
	global_load_dwordx4 v[150:153], v[136:137], off
	s_nop 0
	global_load_dwordx4 v[134:137], v[134:135], off offset:16
	v_addc_co_u32_e32 v143, vcc, 0, v143, vcc
	global_load_dwordx4 v[154:157], v[140:141], off
	s_nop 0
	global_load_dwordx4 v[138:141], v[138:139], off offset:16
	s_nop 0
	global_load_dwordx4 v[158:161], v[142:143], off
	s_nop 0
	global_load_dwordx4 v[142:145], v[144:145], off offset:16
	s_lshl_b32 s19, s0, 4
	s_bfe_i32 s0, s0, 0x1001b
	s_lshr_b32 s0, s0, 19
	s_add_i32 s0, s19, s0
	s_and_b32 s0, s0, 0xffffe000
	s_sub_i32 s10, s19, s0
	v_readlane_b32 s0, v255, 6
	s_cmp_gt_i32 s10, 0
	v_readlane_b32 s1, v255, 7
	s_cselect_b64 s[8:9], -1, 0
	s_cmp_lt_i32 s10, 1
	v_lshl_add_u64 v[174:175], v[178:179], 1, s[0:1]
	s_cbranch_scc1 .LBB0_542
	s_add_i32 s0, s19, -3
	v_mad_i64_i32 v[162:163], s[0:1], s0, v237, v[174:175]
	global_load_dwordx4 v[162:165], v[162:163], off
	s_branch .LBB0_543

; #define D1_LOAD(RH, RV, IT) do { const int it_ = (IT); const int s_ = it_ % 6, m0_ = (it_ / 6) * 16, ch_ = 512 * s_ + 8 * lane; \
;         _Pragma("unroll") for (int tt = 0; tt < 16; ++tt) RV[tt] = *(gcu)(PROJ + (size_t)(m0_ + tt) * NPROJ + ch_); } while (0)
; DI void d1_phase(const Params& P, int l, int gw, int NGW, int lane) {
;     ...
;             if (it + 2 * NGW < NIT) D1_LOAD(hA, vA, it + 2 * NGW);
.LBB0_547:
	s_cmpk_gt_i32 s14, 0x17ff
	s_cbranch_scc1 .Ld1b_nonext
	global_load_dwordx4 v[0:3], v[0:1], off
	global_load_dwordx4 v[4:7], v[4:5], off
	global_load_dwordx4 v[8:11], v[8:9], off
	global_load_dwordx4 v[12:15], v[12:13], off
	global_load_dwordx4 v[16:19], v[16:17], off
	global_load_dwordx4 v[20:23], v[20:21], off
	global_load_dwordx4 v[24:27], v[24:25], off
	global_load_dwordx4 v[28:31], v[28:29], off
	global_load_dwordx4 v[32:35], v[32:33], off
	global_load_dwordx4 v[36:39], v[36:37], off
	global_load_dwordx4 v[40:43], v[40:41], off
	global_load_dwordx4 v[44:47], v[44:45], off
	global_load_dwordx4 v[48:51], v[48:49], off
	global_load_dwordx4 v[52:55], v[52:53], off
	global_load_dwordx4 v[56:59], v[58:59], off
	global_load_dwordx4 v[60:63], v[60:61], off
	s_waitcnt vmcnt(16)
	s_branch .Ld1b_go

.Ld1b_go:
	v_lshlrev_b32_e32 v206, 16, v170
	v_and_b32_e32 v207, 0xffff0000, v170
	v_and_b32_e32 v205, 0xffff0000, v171
	v_lshlrev_b32_e32 v204, 16, v171
	v_and_b32_e32 v181, 0xffff0000, v172
	v_lshlrev_b32_e32 v180, 16, v172
	v_and_b32_e32 v171, 0xffff0000, v173
	v_lshlrev_b32_e32 v170, 16, v173
	v_lshlrev_b32_e32 v172, 16, v162
	v_and_b32_e32 v173, 0xffff0000, v162
	v_pk_mul_f32 v[202:203], v[150:151], v[206:207]
	v_lshlrev_b32_e32 v208, 16, v166
	v_and_b32_e32 v209, 0xffff0000, v166
	v_pk_fma_f32 v[172:173], v[146:147], v[172:173], v[202:203]
	v_lshlrev_b32_e32 v196, 16, v64
	v_and_b32_e32 v197, 0xffff0000, v64
	v_pk_fma_f32 v[172:173], v[154:155], v[208:209], v[172:173]
	v_and_b32_e32 v177, 0xffff0000, v169
	v_pk_fma_f32 v[172:173], v[158:159], v[196:197], v[172:173]
	v_lshlrev_b32_e32 v176, 16, v169
	v_mul_f32_e32 v169, 0xbfb8aa3b, v172
	v_exp_f32_e32 v169, v169
	v_and_b32_e32 v185, 0xffff0000, v163
	v_lshlrev_b32_e32 v184, 16, v163
	v_and_b32_e32 v201, 0xffff0000, v167
	v_add_f32_e32 v169, 1.0, v169
	v_rcp_f32_e32 v202, v169
	v_mul_f32_e32 v169, 0xbfb8aa3b, v173
	v_exp_f32_e32 v169, v169
	v_lshlrev_b32_e32 v200, 16, v167
	v_and_b32_e32 v175, 0xffff0000, v65
	v_lshlrev_b32_e32 v174, 16, v65
	v_add_f32_e32 v169, 1.0, v169
	v_rcp_f32_e32 v203, v169
	v_and_b32_e32 v163, 0xffff0000, v164
	v_lshlrev_b32_e32 v162, 16, v164
	v_and_b32_e32 v199, 0xffff0000, v168
	v_pk_mul_f32 v[172:173], v[172:173], v[202:203]
	v_pk_mul_f32 v[202:203], v[152:153], v[204:205]
	v_lshlrev_b32_e32 v198, 16, v168
	v_pk_fma_f32 v[184:185], v[148:149], v[184:185], v[202:203]
	v_and_b32_e32 v167, 0xffff0000, v66
	v_pk_fma_f32 v[184:185], v[156:157], v[200:201], v[184:185]
	v_lshlrev_b32_e32 v166, 16, v66
	v_pk_fma_f32 v[184:185], v[160:161], v[174:175], v[184:185]
	v_and_b32_e32 v187, 0xffff0000, v165
	v_mul_f32_e32 v169, 0xbfb8aa3b, v184
	v_exp_f32_e32 v169, v169
	v_lshlrev_b32_e32 v186, 16, v165
	v_and_b32_e32 v165, 0xffff0000, v67
	v_lshlrev_b32_e32 v164, 16, v67
	v_add_f32_e32 v169, 1.0, v169
	v_rcp_f32_e32 v202, v169
	v_mul_f32_e32 v169, 0xbfb8aa3b, v185
	v_exp_f32_e32 v169, v169
	s_ashr_i32 s19, s20, 1
	s_cmp_lt_u32 s20, 2
	s_cselect_b64 vcc, -1, 0
	v_add_f32_e32 v169, 1.0, v169
	v_rcp_f32_e32 v203, v169
	s_cmp_lt_i32 s19, 2
	s_cselect_b64 s[8:9], -1, 0
	s_cmp_gt_i32 s19, 1
	v_pk_mul_f32 v[202:203], v[184:185], v[202:203]
	v_pk_mul_f32 v[184:185], v[134:135], v[180:181]
	v_mov_b32_e32 v168, 1.0
	v_pk_fma_f32 v[162:163], v[130:131], v[162:163], v[184:185]
	v_cndmask_b32_e32 v219, 1.0, v238, vcc
	v_pk_fma_f32 v[162:163], v[138:139], v[198:199], v[162:163]
	v_mov_b32_e32 v214, 1.0
	v_pk_fma_f32 v[162:163], v[142:143], v[166:167], v[162:163]
	s_nop 0
	v_mul_f32_e32 v169, 0xbfb8aa3b, v162
	v_exp_f32_e32 v169, v169
	s_nop 0
	v_add_f32_e32 v169, 1.0, v169
	v_rcp_f32_e32 v184, v169
	v_mul_f32_e32 v169, 0xbfb8aa3b, v163
	v_exp_f32_e32 v169, v169
	s_nop 0
	v_add_f32_e32 v169, 1.0, v169
	v_rcp_f32_e32 v185, v169
	s_nop 0
	v_pk_mul_f32 v[210:211], v[162:163], v[184:185]
	v_pk_mul_f32 v[162:163], v[136:137], v[170:171]
	s_nop 0
	v_pk_fma_f32 v[162:163], v[132:133], v[186:187], v[162:163]
	s_nop 0
	v_pk_fma_f32 v[162:163], v[140:141], v[176:177], v[162:163]
	s_nop 0
	v_pk_fma_f32 v[162:163], v[144:145], v[164:165], v[162:163]
	s_nop 0
	v_mul_f32_e32 v169, 0xbfb8aa3b, v162
	v_exp_f32_e32 v169, v169
	s_nop 0
	v_add_f32_e32 v169, 1.0, v169
	v_rcp_f32_e32 v184, v169
	v_mul_f32_e32 v169, 0xbfb8aa3b, v163
	v_exp_f32_e32 v169, v169
	s_nop 0
	v_add_f32_e32 v169, 1.0, v169
	v_rcp_f32_e32 v185, v169
	s_nop 0
	v_pk_mul_f32 v[212:213], v[162:163], v[184:185]
	s_cbranch_scc1 .LBB0_549
	v_pk_mul_f32 v[162:163], v[172:173], v[172:173]
	v_pk_mul_f32 v[184:185], v[202:203], v[202:203]
	v_add_f32_e32 v162, v162, v163
	v_add_f32_e32 v162, v184, v162
	v_pk_mul_f32 v[186:187], v[210:211], v[210:211]
	v_add_f32_e32 v162, v185, v162
	v_and_b32_e32 v169, 64, v232
	v_add_f32_e32 v162, v186, v162
	v_xor_b32_e32 v163, 1, v232
	v_add_u32_e32 v169, 64, v169
	v_pk_mul_f32 v[214:215], v[212:213], v[212:213]
	v_add_f32_e32 v162, v187, v162
	v_cmp_lt_i32_e64 s[0:1], v163, v169
	v_add_f32_e32 v162, v214, v162
	v_add_f32_e32 v162, v215, v162
	v_cndmask_b32_e64 v163, v232, v163, s[0:1]
	v_lshlrev_b32_e32 v163, 2, v163
	ds_bpermute_b32 v163, v163, v162
	s_waitcnt lgkmcnt(0)
	v_add_f32_e32 v162, v162, v163
	v_xor_b32_e32 v163, 2, v232
	v_cmp_lt_i32_e64 s[0:1], v163, v169
	s_nop 1
	v_cndmask_b32_e64 v163, v232, v163, s[0:1]
	v_lshlrev_b32_e32 v163, 2, v163
	ds_bpermute_b32 v163, v163, v162
	s_waitcnt lgkmcnt(0)
	v_add_f32_e32 v162, v162, v163
	v_xor_b32_e32 v163, 4, v232
	v_cmp_lt_i32_e64 s[0:1], v163, v169
	s_nop 1
	v_cndmask_b32_e64 v163, v232, v163, s[0:1]
	v_lshlrev_b32_e32 v163, 2, v163
	ds_bpermute_b32 v163, v163, v162
	s_waitcnt lgkmcnt(0)
	v_add_f32_e32 v162, v162, v163
	v_xor_b32_e32 v163, 8, v232
	v_cmp_lt_i32_e64 s[0:1], v163, v169
	s_nop 1
	v_cndmask_b32_e64 v163, v232, v163, s[0:1]
	v_lshlrev_b32_e32 v163, 2, v163
	ds_bpermute_b32 v163, v163, v162
	s_waitcnt lgkmcnt(0)
	v_add_f32_e32 v162, v162, v163
	v_add_f32_e32 v162, 0x358637bd, v162
	v_rsq_f32_e32 v162, v162
	s_nop 0
	v_mul_f32_e32 v214, v219, v162
